# stacks MLA QK fragment-read hoisting (spare VGPRs, counted lgkmcnt) and S5 pass-1 counted vmcnt on top of the prefetch version
# baseline (speedup 1.0000x reference)
; DEV f32x4 mfma16(bf16x8 a, bf16x8 b, f32x4 c) { return __builtin_amdgcn_mfma_f32_16x16x32_bf16(a, b, c, 0, 0, 0); }
; DEV void s5_item(const Params& p, int l, int item) {
;     ...
;     for (int sc = 0; sc < 18; ++sc) {
;       const int s0 = sbase + sc * 16;
; #pragma unroll
;       for (int tl = 0; tl < 8; ++tl) {
;         f32x4 d = mfma16(uf, bbf[tl], (f32x4){0.f, 0.f, 0.f, 0.f});
; #pragma unroll
;         for (int r = 0; r < 4; ++r) Bu[(fq * 4 + r) * BUP + tl * 16 + fr] = d[r];
;       }
;       if (sc + 1 < 18) { if (fq < 2) uf = ldg8(PROJ + (size_t)s5_token(b, dir, s0 + 16 + fr) * INP + C_U + g * 16 + fq * 8); }
.LBB0_466:
	s_waitcnt lgkmcnt(1)
	s_cmp_eq_u32 s57, 0
	s_cbranch_scc1 .Ls5_w0
	s_cmp_eq_u64 s[50:51], 0
	s_cbranch_scc1 .Ls5_w0
	s_waitcnt vmcnt(1)
	s_branch .Ls5_wd

; DEV f32x4 mfma16(bf16x8 a, bf16x8 b, f32x4 c) { return __builtin_amdgcn_mfma_f32_16x16x32_bf16(a, b, c, 0, 0, 0); }
; DEV void s5_item(const Params& p, int l, int item) {
;     ...
; #pragma unroll
;       for (int tl = 0; tl < 8; ++tl) {
;         f32x4 d = mfma16(uf, bbf[tl], (f32x4){0.f, 0.f, 0.f, 0.f});
; #pragma unroll
;         for (int r = 0; r < 4; ++r) Bu[(fq * 4 + r) * BUP + tl * 16 + fr] = d[r];
;       }
;       if (sc + 1 < 18) { if (fq < 2) uf = ldg8(PROJ + (size_t)s5_token(b, dir, s0 + 16 + fr) * INP + C_U + g * 16 + fq * 8); }
.Ls5_wd:
	v_mfma_f32_16x16x32_bf16 v[72:75], v[52:55], v[20:23], 0
	s_waitcnt lgkmcnt(0)
	v_add_u32_e32 v2, 0x400, v106
	s_cmpk_lg_i32 s57, 0x110
	s_cselect_b64 s[52:53], -1, 0
	v_mfma_f32_16x16x32_bf16 v[76:79], v[52:55], v[12:15], 0
	s_nop 7
	ds_write2_b32 v106, v72, v76 offset1:16
	ds_write2_b32 v106, v73, v77 offset0:132 offset1:148
	ds_write2_b32 v2, v74, v78 offset0:8 offset1:24
	ds_write2_b32 v2, v75, v79 offset0:140 offset1:156
	v_mfma_f32_16x16x32_bf16 v[72:75], v[52:55], v[4:7], 0
	s_and_b64 s[58:59], s[38:39], s[52:53]
	v_mfma_f32_16x16x32_bf16 v[76:79], v[52:55], v[28:31], 0
	s_nop 7
	ds_write2_b32 v106, v72, v76 offset0:32 offset1:48
	ds_write2_b32 v106, v73, v77 offset0:164 offset1:180
	ds_write2_b32 v2, v74, v78 offset0:40 offset1:56
	ds_write2_b32 v2, v75, v79 offset0:172 offset1:188
	v_mfma_f32_16x16x32_bf16 v[72:75], v[52:55], v[24:27], 0
	v_mfma_f32_16x16x32_bf16 v[76:79], v[52:55], v[16:19], 0
	s_nop 7
	ds_write2_b32 v106, v72, v76 offset0:64 offset1:80
	ds_write2_b32 v106, v73, v77 offset0:196 offset1:212
	ds_write2_b32 v2, v74, v78 offset0:72 offset1:88
	ds_write2_b32 v2, v75, v79 offset0:204 offset1:220
	v_mfma_f32_16x16x32_bf16 v[72:75], v[52:55], v[8:11], 0
	v_mfma_f32_16x16x32_bf16 v[76:79], v[52:55], v[32:35], 0
	s_nop 7
	ds_write2_b32 v106, v72, v76 offset0:96 offset1:112
	ds_write2_b32 v106, v73, v77 offset0:228 offset1:244
	ds_write2_b32 v2, v74, v78 offset0:104 offset1:120
	ds_write2_b32 v2, v75, v79 offset0:236 offset1:252
	s_and_saveexec_b64 s[52:53], s[58:59]
	s_cbranch_execz .LBB0_468
	v_add_u32_e32 v2, s57, v103
	v_add_u32_e32 v3, 16, v2
	v_cmp_gt_i32_e32 vcc, s33, v3
	v_add_u32_e32 v2, 0xffffff10, v2
	v_mov_b32_e32 v53, s56
	v_cndmask_b32_e32 v52, v212, v213, vcc
	v_cndmask_b32_e32 v2, v2, v3, vcc
	v_mov_b32_e32 v3, s41
	v_add3_u32 v52, v52, v0, -16
	v_cndmask_b32_e32 v3, v3, v53, vcc
	v_cndmask_b32_e64 v2, v52, v2, s[0:1]
	v_add_u32_e32 v2, v2, v3
	v_mad_i64_i32 v[2:3], s[58:59], v2, s96, v[68:69]
	global_load_dwordx4 v[52:55], v[2:3], off offset:832

; DEV f32x4 mfma16(bf16x8 a, bf16x8 b, f32x4 c) { return __builtin_amdgcn_mfma_f32_16x16x32_bf16(a, b, c, 0, 0, 0); }
; template <int KS>
; DEV void attn_chunk(const unsigned char* Kl, const unsigned char* Vl, const bf16x8 (&qf)[2][KS], f32x4 (&O)[2][4], float (&mrun)[2], float (&lrun)[2],
;                     bool masked, int key0, int qw0, float sl2, int lane, int fr, int fq) {
;     ...
;   f32x4 sc[2][4];
; #pragma unroll
;   for (int kt = 0; kt < 4; ++kt) {
;     sc[0][kt] = (f32x4){0.f, 0.f, 0.f, 0.f}; sc[1][kt] = (f32x4){0.f, 0.f, 0.f, 0.f};
; #pragma unroll
;     for (int kk = 0; kk < KS; ++kk) {
;       bf16x8 kf = *reinterpret_cast<const bf16x8*>(Kl + ((kt * 16 + fr) * KP + kk * 32 + fq * 8) * 2);
;       sc[0][kt] = mfma16(kf, qf[0][kk], sc[0][kt]); sc[1][kt] = mfma16(kf, qf[1][kk], sc[1][kt]);
;     }
;   }
;   bf16x8 pf[2][2];
; #pragma unroll
;   for (int qi = 0; qi < 2; ++qi) {
;     float mx = -1e30f;
; #pragma unroll
;     for (int kt = 0; kt < 4; ++kt)
; #pragma unroll
;       for (int r = 0; r < 4; ++r) { float v = sc[qi][kt][r] * sl2;
;         if (masked) { int kp = key0 + kt * 16 + fq * 4 + r; int dq = qw0 + qi * 16 + fr - kp; if (dq > 128 || dq < -128) v = -1e30f; }
;         sc[qi][kt][r] = v; mx = fmaxf(mx, v); }
;     mx = max_x16_x32(mx);
;     const float mnew = fmaxf(mrun[qi], mx);
;     const float alpha = __builtin_amdgcn_exp2f(mrun[qi] - mnew);
;     mrun[qi] = mnew;
;     float ps = 0.f;
; #pragma unroll
;     for (int kt = 0; kt < 4; ++kt)
; #pragma unroll
;       for (int r = 0; r < 4; ++r) { float pvv = __builtin_amdgcn_exp2f(sc[qi][kt][r] - mnew); ps += pvv; sc[qi][kt][r] = pvv; }
;     pf[qi][0] = pack8(sc[qi][0][0], sc[qi][0][1], sc[qi][0][2], sc[qi][0][3], sc[qi][1][0], sc[qi][1][1], sc[qi][1][2], sc[qi][1][3]);
;     pf[qi][1] = pack8(sc[qi][2][0], sc[qi][2][1], sc[qi][2][2], sc[qi][2][3], sc[qi][3][0], sc[qi][3][1], sc[qi][3][2], sc[qi][3][3]);
.LBB0_616:
	ds_read_b128 v[82:85], v202
	ds_read_b128 v[90:93], v202 offset:64
	ds_read_b128 v[222:225], v202 offset:128
	ds_read_b128 v[226:229], v202 offset:3328
	ds_read_b128 v[98:101], v202 offset:3392
	ds_read_b128 v[230:233], v202 offset:3456
	ds_read_b128 v[234:237], v202 offset:6656
	ds_read_b128 v[102:105], v202 offset:6720
	ds_read_b128 v[238:241], v202 offset:6784
	ds_read_b128 v[242:245], v202 offset:9984
	ds_read_b128 v[122:125], v202 offset:10048
	ds_read_b128 v[246:249], v202 offset:10112
	s_mov_b32 s0, 0xf149f2ca
	s_mov_b32 s1, 0x3e16c740
	s_waitcnt lgkmcnt(11)
	v_mfma_f32_16x16x32_bf16 v[86:89], v[82:85], v[2:5], 0
	v_mfma_f32_16x16x32_bf16 v[82:85], v[82:85], v[18:21], 0
	s_waitcnt lgkmcnt(10)
	v_mfma_f32_16x16x32_bf16 v[86:89], v[90:93], v[6:9], v[86:89]
	v_mfma_f32_16x16x32_bf16 v[82:85], v[90:93], v[14:17], v[82:85]
	s_waitcnt lgkmcnt(9)
	v_mfma_f32_16x16x32_bf16 v[86:89], v[222:225], v[10:13], v[86:89]
	v_mfma_f32_16x16x32_bf16 v[90:93], v[222:225], v[22:25], v[82:85]
	s_waitcnt lgkmcnt(8)
	v_mfma_f32_16x16x32_bf16 v[94:97], v[226:229], v[2:5], 0
	v_mfma_f32_16x16x32_bf16 v[82:85], v[226:229], v[18:21], 0
	s_waitcnt lgkmcnt(7)
	v_mfma_f32_16x16x32_bf16 v[94:97], v[98:101], v[6:9], v[94:97]
	v_mfma_f32_16x16x32_bf16 v[82:85], v[98:101], v[14:17], v[82:85]
	s_waitcnt lgkmcnt(6)
	v_mfma_f32_16x16x32_bf16 v[132:135], v[230:233], v[10:13], v[94:97]
	v_mfma_f32_16x16x32_bf16 v[94:97], v[230:233], v[22:25], v[82:85]
	s_waitcnt lgkmcnt(5)
	v_mfma_f32_16x16x32_bf16 v[98:101], v[234:237], v[2:5], 0
	v_mfma_f32_16x16x32_bf16 v[82:85], v[234:237], v[18:21], 0
	s_waitcnt lgkmcnt(4)
	v_mfma_f32_16x16x32_bf16 v[98:101], v[102:105], v[6:9], v[98:101]
	v_mfma_f32_16x16x32_bf16 v[82:85], v[102:105], v[14:17], v[82:85]
	s_waitcnt lgkmcnt(3)
	v_mfma_f32_16x16x32_bf16 v[140:143], v[238:241], v[10:13], v[98:101]
	v_mfma_f32_16x16x32_bf16 v[98:101], v[238:241], v[22:25], v[82:85]
	s_waitcnt lgkmcnt(2)
	v_mfma_f32_16x16x32_bf16 v[102:105], v[242:245], v[2:5], 0
	v_mfma_f32_16x16x32_bf16 v[82:85], v[242:245], v[18:21], 0
	s_waitcnt lgkmcnt(1)
	v_mfma_f32_16x16x32_bf16 v[102:105], v[122:125], v[6:9], v[102:105]
	v_mfma_f32_16x16x32_bf16 v[82:85], v[122:125], v[14:17], v[82:85]
	s_waitcnt lgkmcnt(0)
	v_mfma_f32_16x16x32_bf16 v[148:151], v[246:249], v[10:13], v[102:105]
	v_mfma_f32_16x16x32_bf16 v[102:105], v[246:249], v[22:25], v[82:85]
	v_mul_f32_e32 v127, 0x3e16c740, v93
	v_mul_f32_e32 v123, 0x3e16c740, v90
	v_mul_f32_e32 v125, 0x3e16c740, v91
	v_max3_f32 v123, v123, s0, v125
	s_nop 0
	v_mul_f32_e32 v82, 0x3e16c740, v86
	v_mul_f32_e32 v83, 0x3e16c740, v87
	v_max3_f32 v82, v82, s0, v83
	v_mul_f32_e32 v83, 0x3e16c740, v88
	v_mul_f32_e32 v84, 0x3e16c740, v89
	v_max3_f32 v82, v82, v83, v84
	v_mul_f32_e32 v83, 0x3e16c740, v132
	v_mul_f32_e32 v84, 0x3e16c740, v133
	v_max3_f32 v82, v82, v83, v84
	v_mul_f32_e32 v83, 0x3e16c740, v134
	v_mul_f32_e32 v84, 0x3e16c740, v135
	v_max3_f32 v82, v82, v83, v84
	v_mul_f32_e32 v83, 0x3e16c740, v140
	v_mul_f32_e32 v84, 0x3e16c740, v141
	v_max3_f32 v82, v82, v83, v84
	v_mul_f32_e32 v83, 0x3e16c740, v142
	v_mul_f32_e32 v84, 0x3e16c740, v143
	v_max3_f32 v82, v82, v83, v84
	v_mul_f32_e32 v83, 0x3e16c740, v148
	v_mul_f32_e32 v84, 0x3e16c740, v149
	v_max3_f32 v82, v82, v83, v84
	v_mul_f32_e32 v83, 0x3e16c740, v150
	v_mul_f32_e32 v84, 0x3e16c740, v151
	v_max3_f32 v82, v82, v83, v84
	v_mul_f32_e32 v125, 0x3e16c740, v92
	v_mov_b32_e32 v83, v82
	v_max3_f32 v123, v123, v125, v127
	v_mul_f32_e32 v125, 0x3e16c740, v94
	v_mul_f32_e32 v127, 0x3e16c740, v95
	v_permlane32_swap_b32_e32 v82, v83
	v_max3_f32 v123, v123, v125, v127
	v_mul_f32_e32 v125, 0x3e16c740, v96
	v_mul_f32_e32 v127, 0x3e16c740, v97
	v_max_f32_e32 v83, v83, v83
	v_max_f32_e32 v82, v82, v82
	v_max3_f32 v123, v123, v125, v127
	v_mul_f32_e32 v125, 0x3e16c740, v98
	v_mul_f32_e32 v127, 0x3e16c740, v99
	v_max_f32_e32 v82, v82, v83
	v_max3_f32 v123, v123, v125, v127
	v_mul_f32_e32 v125, 0x3e16c740, v100
	v_mul_f32_e32 v127, 0x3e16c740, v101
	v_mov_b32_e32 v83, v82
	v_max3_f32 v123, v123, v125, v127
	v_mul_f32_e32 v125, 0x3e16c740, v102
	v_mul_f32_e32 v127, 0x3e16c740, v103
	v_permlane16_swap_b32_e32 v82, v83
	v_max3_f32 v123, v123, v125, v127
	v_mul_f32_e32 v125, 0x3e16c740, v104
	v_mul_f32_e32 v127, 0x3e16c740, v105
	v_max3_f32 v156, v218, v82, v83
	v_max3_f32 v123, v123, v125, v127
	v_fma_f32 v83, v86, s1, -v156
	v_mov_b32_e32 v125, v123
	v_exp_f32_e32 v122, v83
	v_fma_f32 v83, v87, s1, -v156
	v_permlane32_swap_b32_e32 v123, v125
	v_exp_f32_e32 v126, v83
	v_fma_f32 v83, v88, s1, -v156
	v_max_f32_e32 v125, v125, v125
	v_max_f32_e32 v123, v123, v123
	v_exp_f32_e32 v124, v83
	v_fma_f32 v83, v89, s1, -v156
	v_max_f32_e32 v123, v123, v125
	v_exp_f32_e32 v128, v83
	v_fma_f32 v83, v132, s1, -v156
	v_mov_b32_e32 v125, v123
	v_exp_f32_e32 v132, v83
	v_fma_f32 v83, v133, s1, -v156
	v_permlane16_swap_b32_e32 v123, v125
	v_exp_f32_e32 v130, v83
	v_fma_f32 v83, v134, s1, -v156
	v_max3_f32 v157, v219, v123, v125
	v_exp_f32_e32 v134, v83
	v_fma_f32 v83, v135, s1, -v156
	v_fma_f32 v90, v90, s1, -v157
	v_exp_f32_e32 v138, v83
	v_fma_f32 v83, v140, s1, -v156
	v_exp_f32_e32 v123, v90
	v_fma_f32 v90, v91, s1, -v157
	v_sub_f32_e32 v82, v218, v156
; DEV f32x4 mfma16(bf16x8 a, bf16x8 b, f32x4 c) { return __builtin_amdgcn_mfma_f32_16x16x32_bf16(a, b, c, 0, 0, 0); }
; template <int KS>
; DEV void attn_chunk(const unsigned char* Kl, const unsigned char* Vl, const bf16x8 (&qf)[2][KS], f32x4 (&O)[2][4], float (&mrun)[2], float (&lrun)[2],
;                     bool masked, int key0, int qw0, float sl2, int lane, int fr, int fq) {
;     ...
;     float ps = 0.f;
; #pragma unroll
;     for (int kt = 0; kt < 4; ++kt)
; #pragma unroll
;       for (int r = 0; r < 4; ++r) { float pvv = __builtin_amdgcn_exp2f(sc[qi][kt][r] - mnew); ps += pvv; sc[qi][kt][r] = pvv; }
;     pf[qi][0] = pack8(sc[qi][0][0], sc[qi][0][1], sc[qi][0][2], sc[qi][0][3], sc[qi][1][0], sc[qi][1][1], sc[qi][1][2], sc[qi][1][3]);
;     pf[qi][1] = pack8(sc[qi][2][0], sc[qi][2][1], sc[qi][2][2], sc[qi][2][3], sc[qi][3][0], sc[qi][3][1], sc[qi][3][2], sc[qi][3][3]);
;     lrun[qi] = lrun[qi] * alpha + ps;
; #pragma unroll
;     for (int dt = 0; dt < 4; ++dt) O[qi][dt] *= alpha;
;   }
; #pragma unroll
;   for (int dt = 0; dt < 4; ++dt)
; #pragma unroll
;     for (int sub = 0; sub < 2; ++sub) {
;       const unsigned char* vp = Vl + ((dt * 16 + fr) * VP + sub * 32 + fq * 4) * 2;
;       u32x2 v0 = *reinterpret_cast<const u32x2*>(vp), v1 = *reinterpret_cast<const u32x2*>(vp + 32);
;       u32x4 vv = {v0[0], v0[1], v1[0], v1[1]};
;       bf16x8 vf = *reinterpret_cast<bf16x8*>(&vv);
;       O[0][dt] = mfma16(vf, pf[0][sub], O[0][dt]); O[1][dt] = mfma16(vf, pf[1][sub], O[1][dt]);
;     }
	v_exp_f32_e32 v136, v83
	v_fma_f32 v83, v141, s1, -v156
	v_exp_f32_e32 v127, v90
	v_fma_f32 v90, v92, s1, -v157
	v_exp_f32_e32 v140, v83
	v_fma_f32 v83, v142, s1, -v156
	v_exp_f32_e32 v142, v82
	v_exp_f32_e32 v125, v90
	v_fma_f32 v90, v93, s1, -v157
	v_exp_f32_e32 v129, v90
	v_fma_f32 v90, v94, s1, -v157
	v_exp_f32_e32 v133, v90
	v_fma_f32 v90, v95, s1, -v157
	v_exp_f32_e32 v131, v90
	v_fma_f32 v90, v96, s1, -v157
	v_exp_f32_e32 v146, v83
	v_fma_f32 v83, v143, s1, -v156
	v_pk_mul_f32 v[68:69], v[68:69], v[142:143] op_sel_hi:[1,0]
	v_pk_mul_f32 v[66:67], v[66:67], v[142:143] op_sel_hi:[1,0]
	v_pk_mul_f32 v[72:73], v[72:73], v[142:143] op_sel_hi:[1,0]
	v_pk_mul_f32 v[70:71], v[70:71], v[142:143] op_sel_hi:[1,0]
	v_pk_mul_f32 v[76:77], v[76:77], v[142:143] op_sel_hi:[1,0]
	v_pk_mul_f32 v[74:75], v[74:75], v[142:143] op_sel_hi:[1,0]
	v_pk_mul_f32 v[80:81], v[80:81], v[142:143] op_sel_hi:[1,0]
	v_pk_mul_f32 v[78:79], v[78:79], v[142:143] op_sel_hi:[1,0]
	v_sub_f32_e32 v143, v219, v157
	v_exp_f32_e32 v135, v90
	v_fma_f32 v90, v97, s1, -v157
	v_exp_f32_e32 v139, v90
	v_fma_f32 v90, v98, s1, -v157
	v_exp_f32_e32 v143, v143
	v_exp_f32_e32 v137, v90
	v_fma_f32 v90, v99, s1, -v157
	v_exp_f32_e32 v141, v90
	v_fma_f32 v90, v100, s1, -v157
	v_exp_f32_e32 v147, v90
	v_fma_f32 v90, v101, s1, -v157
	v_exp_f32_e32 v145, v90
	v_fma_f32 v90, v102, s1, -v157
	v_mov_b32_e32 v98, v143
	v_add_u32_e32 v102, 0x6800, v203
	v_pk_mul_f32 v[52:53], v[52:53], v[98:99] op_sel_hi:[1,0]
	v_pk_mul_f32 v[50:51], v[50:51], v[98:99] op_sel_hi:[1,0]
	v_pk_mul_f32 v[56:57], v[56:57], v[98:99] op_sel_hi:[1,0]
	v_pk_mul_f32 v[54:55], v[54:55], v[98:99] op_sel_hi:[1,0]
	v_pk_mul_f32 v[60:61], v[60:61], v[98:99] op_sel_hi:[1,0]
	v_pk_mul_f32 v[58:59], v[58:59], v[98:99] op_sel_hi:[1,0]
	v_pk_mul_f32 v[64:65], v[64:65], v[98:99] op_sel_hi:[1,0]
	v_pk_mul_f32 v[62:63], v[62:63], v[98:99] op_sel_hi:[1,0]
	ds_read2_b64 v[98:101], v102 offset1:4
	v_cvt_pk_bf16_f32 v86, v122, v126
	v_cvt_pk_bf16_f32 v87, v124, v128
	v_cvt_pk_bf16_f32 v88, v132, v130
	v_cvt_pk_bf16_f32 v89, v134, v138
	v_cvt_pk_bf16_f32 v94, v123, v127
	v_cvt_pk_bf16_f32 v95, v125, v129
	v_cvt_pk_bf16_f32 v96, v133, v131
	v_cvt_pk_bf16_f32 v97, v135, v139
	v_exp_f32_e32 v144, v83
	v_fma_f32 v83, v148, s1, -v156
	s_waitcnt lgkmcnt(0)
	v_mfma_f32_16x16x32_bf16 v[66:69], v[98:101], v[86:89], v[66:69]
	v_exp_f32_e32 v154, v83
	v_fma_f32 v83, v149, s1, -v156
	v_exp_f32_e32 v155, v90
	v_mfma_f32_16x16x32_bf16 v[50:53], v[98:101], v[94:97], v[50:53]
	ds_read2_b64 v[98:101], v102 offset0:8 offset1:12
	v_fma_f32 v90, v103, s1, -v157
	v_exp_f32_e32 v152, v83
	v_fma_f32 v83, v150, s1, -v156
	v_exp_f32_e32 v153, v90
	v_fma_f32 v90, v104, s1, -v157
	v_exp_f32_e32 v150, v83
	v_fma_f32 v83, v151, s1, -v156
	v_exp_f32_e32 v151, v90
	v_fma_f32 v90, v105, s1, -v157
	v_exp_f32_e32 v148, v83
	v_exp_f32_e32 v149, v90
	v_cvt_pk_bf16_f32 v82, v136, v140
	v_cvt_pk_bf16_f32 v83, v146, v144
	v_cvt_pk_bf16_f32 v84, v154, v152
	v_cvt_pk_bf16_f32 v85, v150, v148
	v_cvt_pk_bf16_f32 v90, v137, v141
	v_cvt_pk_bf16_f32 v91, v147, v145
	v_cvt_pk_bf16_f32 v92, v155, v153
	v_cvt_pk_bf16_f32 v93, v151, v149
	v_add_u32_e32 v102, 0x7000, v203
	s_waitcnt lgkmcnt(0)
	v_mfma_f32_16x16x32_bf16 v[66:69], v[98:101], v[82:85], v[66:69]
	v_mfma_f32_16x16x32_bf16 v[50:53], v[98:101], v[90:93], v[50:53]
	ds_read2_b64 v[98:101], v102 offset0:32 offset1:36
	s_waitcnt lgkmcnt(0)
	v_mfma_f32_16x16x32_bf16 v[70:73], v[98:101], v[86:89], v[70:73]
	v_mfma_f32_16x16x32_bf16 v[54:57], v[98:101], v[94:97], v[54:57]
	ds_read2_b64 v[98:101], v102 offset0:40 offset1:44
	v_add_u32_e32 v102, 0x7800, v203
	s_waitcnt lgkmcnt(0)
	v_mfma_f32_16x16x32_bf16 v[70:73], v[98:101], v[82:85], v[70:73]
	v_mfma_f32_16x16x32_bf16 v[54:57], v[98:101], v[90:93], v[54:57]
	ds_read2_b64 v[98:101], v102 offset0:64 offset1:68
	s_waitcnt lgkmcnt(0)
	v_mfma_f32_16x16x32_bf16 v[74:77], v[98:101], v[86:89], v[74:77]
	v_mfma_f32_16x16x32_bf16 v[58:61], v[98:101], v[94:97], v[58:61]
	ds_read2_b64 v[98:101], v102 offset0:72 offset1:76
	v_add_u32_e32 v102, 0x8000, v203
	s_waitcnt lgkmcnt(0)
	v_mfma_f32_16x16x32_bf16 v[74:77], v[98:101], v[82:85], v[74:77]
	v_mfma_f32_16x16x32_bf16 v[58:61], v[98:101], v[90:93], v[58:61]
	ds_read2_b64 v[98:101], v102 offset0:96 offset1:100
	s_waitcnt lgkmcnt(0)
	v_mfma_f32_16x16x32_bf16 v[62:65], v[98:101], v[94:97], v[62:65]
	ds_read2_b64 v[94:97], v102 offset0:104 offset1:108
	s_waitcnt vmcnt(1)
	ds_write_b128 v199, v[38:41] offset:13312
	v_mfma_f32_16x16x32_bf16 v[78:81], v[98:101], v[86:89], v[78:81]
	s_waitcnt lgkmcnt(1)
	v_mfma_f32_16x16x32_bf16 v[86:89], v[94:97], v[82:85], v[78:81]
	v_mfma_f32_16x16x32_bf16 v[62:65], v[94:97], v[90:93], v[62:65]
	s_and_saveexec_b64 s[0:1], s[40:41]
	ds_write_b128 v200, v[42:45] offset:13312
	s_or_b64 exec, exec, s[0:1]
	s_waitcnt vmcnt(0)
	ds_write_b128 v201, v[46:49] offset:35840
	s_waitcnt lgkmcnt(0)
	s_barrier
	v_cndmask_b32_e64 v78, 0, 1, s[52:53]
	v_cmp_ne_u32_e64 s[0:1], 1, v78
	s_andn2_b64 vcc, exec, s[52:53]
	s_cbranch_vccnz .LBB0_622
	global_load_dwordx4 v[38:41], v[116:117], off
	s_and_saveexec_b64 s[48:49], s[40:41]
	s_cbranch_execz .LBB0_621
	global_load_dwordx4 v[42:45], v[118:119], off

; DEV f32x4 mfma16(bf16x8 a, bf16x8 b, f32x4 c) { return __builtin_amdgcn_mfma_f32_16x16x32_bf16(a, b, c, 0, 0, 0); }
; template <int KS>
; DEV void attn_chunk(const unsigned char* Kl, const unsigned char* Vl, const bf16x8 (&qf)[2][KS], f32x4 (&O)[2][4], float (&mrun)[2], float (&lrun)[2],
;                     bool masked, int key0, int qw0, float sl2, int lane, int fr, int fq) {
;     ...
;   f32x4 sc[2][4];
; #pragma unroll
;   for (int kt = 0; kt < 4; ++kt) {
;     sc[0][kt] = (f32x4){0.f, 0.f, 0.f, 0.f}; sc[1][kt] = (f32x4){0.f, 0.f, 0.f, 0.f};
; #pragma unroll
;     for (int kk = 0; kk < KS; ++kk) {
;       bf16x8 kf = *reinterpret_cast<const bf16x8*>(Kl + ((kt * 16 + fr) * KP + kk * 32 + fq * 8) * 2);
;       sc[0][kt] = mfma16(kf, qf[0][kk], sc[0][kt]); sc[1][kt] = mfma16(kf, qf[1][kk], sc[1][kt]);
;     }
;   }
;   bf16x8 pf[2][2];
; #pragma unroll
;   for (int qi = 0; qi < 2; ++qi) {
;     float mx = -1e30f;
; #pragma unroll
;     for (int kt = 0; kt < 4; ++kt)
; #pragma unroll
;       for (int r = 0; r < 4; ++r) { float v = sc[qi][kt][r] * sl2;
;         if (masked) { int kp = key0 + kt * 16 + fq * 4 + r; int dq = qw0 + qi * 16 + fr - kp; if (dq > 128 || dq < -128) v = -1e30f; }
;         sc[qi][kt][r] = v; mx = fmaxf(mx, v); }
;     mx = max_x16_x32(mx);
;     const float mnew = fmaxf(mrun[qi], mx);
;     const float alpha = __builtin_amdgcn_exp2f(mrun[qi] - mnew);
;     mrun[qi] = mnew;
;     float ps = 0.f;
; #pragma unroll
;     for (int kt = 0; kt < 4; ++kt)
; #pragma unroll
;       for (int r = 0; r < 4; ++r) { float pvv = __builtin_amdgcn_exp2f(sc[qi][kt][r] - mnew); ps += pvv; sc[qi][kt][r] = pvv; }
;     pf[qi][0] = pack8(sc[qi][0][0], sc[qi][0][1], sc[qi][0][2], sc[qi][0][3], sc[qi][1][0], sc[qi][1][1], sc[qi][1][2], sc[qi][1][3]);
;     pf[qi][1] = pack8(sc[qi][2][0], sc[qi][2][1], sc[qi][2][2], sc[qi][2][3], sc[qi][3][0], sc[qi][3][1], sc[qi][3][2], sc[qi][3][3]);
.LBB0_622:
	ds_read_b128 v[78:81], v202 offset:13312
	ds_read_b128 v[90:93], v202 offset:13376
	ds_read_b128 v[222:225], v202 offset:13440
	ds_read_b128 v[226:229], v202 offset:16640
	ds_read_b128 v[98:101], v202 offset:16704
	ds_read_b128 v[230:233], v202 offset:16768
	ds_read_b128 v[234:237], v202 offset:19968
	ds_read_b128 v[102:105], v202 offset:20032
	ds_read_b128 v[238:241], v202 offset:20096
	ds_read_b128 v[242:245], v202 offset:23296
	ds_read_b128 v[158:161], v202 offset:23360
	ds_read_b128 v[246:249], v202 offset:23424
	s_mov_b32 s44, 0xf149f2ca
	s_mov_b32 s8, 0x3e16c740
	s_and_b64 vcc, exec, s[0:1]
	s_waitcnt lgkmcnt(11)
	v_mfma_f32_16x16x32_bf16 v[82:85], v[78:81], v[2:5], 0
	v_mfma_f32_16x16x32_bf16 v[78:81], v[78:81], v[18:21], 0
	s_waitcnt lgkmcnt(10)
	v_mfma_f32_16x16x32_bf16 v[82:85], v[90:93], v[6:9], v[82:85]
	v_mfma_f32_16x16x32_bf16 v[78:81], v[90:93], v[14:17], v[78:81]
	s_waitcnt lgkmcnt(9)
	v_mfma_f32_16x16x32_bf16 v[82:85], v[222:225], v[10:13], v[82:85]
	v_mfma_f32_16x16x32_bf16 v[90:93], v[222:225], v[22:25], v[78:81]
	s_waitcnt lgkmcnt(8)
	v_mfma_f32_16x16x32_bf16 v[94:97], v[226:229], v[2:5], 0
	v_mfma_f32_16x16x32_bf16 v[78:81], v[226:229], v[18:21], 0
	s_waitcnt lgkmcnt(7)
	v_mfma_f32_16x16x32_bf16 v[94:97], v[98:101], v[6:9], v[94:97]
	v_mfma_f32_16x16x32_bf16 v[78:81], v[98:101], v[14:17], v[78:81]
	s_waitcnt lgkmcnt(6)
	v_mfma_f32_16x16x32_bf16 v[166:169], v[230:233], v[10:13], v[94:97]
	v_mfma_f32_16x16x32_bf16 v[94:97], v[230:233], v[22:25], v[78:81]
	s_waitcnt lgkmcnt(5)
	v_mfma_f32_16x16x32_bf16 v[98:101], v[234:237], v[2:5], 0
	v_mfma_f32_16x16x32_bf16 v[78:81], v[234:237], v[18:21], 0
	s_waitcnt lgkmcnt(4)
	v_mfma_f32_16x16x32_bf16 v[98:101], v[102:105], v[6:9], v[98:101]
	v_mfma_f32_16x16x32_bf16 v[78:81], v[102:105], v[14:17], v[78:81]
	s_waitcnt lgkmcnt(3)
	v_mfma_f32_16x16x32_bf16 v[174:177], v[238:241], v[10:13], v[98:101]
	v_mfma_f32_16x16x32_bf16 v[98:101], v[238:241], v[22:25], v[78:81]
	s_waitcnt lgkmcnt(2)
	v_mfma_f32_16x16x32_bf16 v[102:105], v[242:245], v[2:5], 0
	v_mfma_f32_16x16x32_bf16 v[78:81], v[242:245], v[18:21], 0
	s_waitcnt lgkmcnt(1)
	v_mfma_f32_16x16x32_bf16 v[102:105], v[158:161], v[6:9], v[102:105]
	v_mfma_f32_16x16x32_bf16 v[78:81], v[158:161], v[14:17], v[78:81]
	s_waitcnt lgkmcnt(0)
	v_mfma_f32_16x16x32_bf16 v[188:191], v[246:249], v[10:13], v[102:105]
	v_mfma_f32_16x16x32_bf16 v[102:105], v[246:249], v[22:25], v[78:81]
	v_mul_f32_e32 v163, 0x3e16c740, v93
	v_mul_f32_e32 v159, 0x3e16c740, v90
	v_mul_f32_e32 v161, 0x3e16c740, v91
	v_max3_f32 v159, v159, s44, v161
	s_nop 0
	v_mul_f32_e32 v78, 0x3e16c740, v82
	v_mul_f32_e32 v79, 0x3e16c740, v83
	v_max3_f32 v78, v78, s44, v79
	v_mul_f32_e32 v79, 0x3e16c740, v84
	v_mul_f32_e32 v80, 0x3e16c740, v85
	v_max3_f32 v78, v78, v79, v80
	v_mul_f32_e32 v79, 0x3e16c740, v166
	v_mul_f32_e32 v80, 0x3e16c740, v167
	v_max3_f32 v78, v78, v79, v80
	v_mul_f32_e32 v79, 0x3e16c740, v168
	v_mul_f32_e32 v80, 0x3e16c740, v169
	v_max3_f32 v78, v78, v79, v80
	v_mul_f32_e32 v79, 0x3e16c740, v174
	v_mul_f32_e32 v80, 0x3e16c740, v175
	v_max3_f32 v78, v78, v79, v80
	v_mul_f32_e32 v79, 0x3e16c740, v176
	v_mul_f32_e32 v80, 0x3e16c740, v177
	v_max3_f32 v78, v78, v79, v80
	v_mul_f32_e32 v79, 0x3e16c740, v188
	v_mul_f32_e32 v80, 0x3e16c740, v189
	v_max3_f32 v78, v78, v79, v80
	v_mul_f32_e32 v79, 0x3e16c740, v190
	v_mul_f32_e32 v80, 0x3e16c740, v191
	v_max3_f32 v78, v78, v79, v80
	v_mov_b32_e32 v79, v78
	s_nop 1
	v_permlane32_swap_b32_e32 v78, v79
	v_max_f32_e32 v79, v79, v79
	v_max_f32_e32 v78, v78, v78
	v_max_f32_e32 v78, v78, v79
	v_mov_b32_e32 v79, v78
	s_nop 1
	v_permlane16_swap_b32_e32 v78, v79
	v_mul_f32_e32 v161, 0x3e16c740, v92
	v_max3_f32 v218, v156, v78, v79
	v_max3_f32 v159, v159, v161, v163
	v_mul_f32_e32 v161, 0x3e16c740, v94
	v_mul_f32_e32 v163, 0x3e16c740, v95
	v_fma_f32 v79, v82, s8, -v218
	v_max3_f32 v159, v159, v161, v163
	v_mul_f32_e32 v161, 0x3e16c740, v96
	v_mul_f32_e32 v163, 0x3e16c740, v97
	v_sub_f32_e32 v78, v156, v218
	v_exp_f32_e32 v156, v79
	v_fma_f32 v79, v83, s8, -v218
	v_max3_f32 v159, v159, v161, v163
	v_mul_f32_e32 v161, 0x3e16c740, v98
	v_mul_f32_e32 v163, 0x3e16c740, v99
	v_exp_f32_e32 v160, v79
	v_fma_f32 v79, v84, s8, -v218
	v_max3_f32 v159, v159, v161, v163
	v_mul_f32_e32 v161, 0x3e16c740, v100
	v_mul_f32_e32 v163, 0x3e16c740, v101
	v_exp_f32_e32 v158, v79
	v_fma_f32 v79, v85, s8, -v218
	v_max3_f32 v159, v159, v161, v163
	v_mul_f32_e32 v161, 0x3e16c740, v102
	v_mul_f32_e32 v163, 0x3e16c740, v103
	v_exp_f32_e32 v162, v79
	v_fma_f32 v79, v166, s8, -v218
	v_max3_f32 v159, v159, v161, v163
	v_mul_f32_e32 v161, 0x3e16c740, v104
	v_mul_f32_e32 v163, 0x3e16c740, v105
	v_exp_f32_e32 v166, v79
	v_fma_f32 v79, v167, s8, -v218
	v_max3_f32 v159, v159, v161, v163
	v_exp_f32_e32 v164, v79
	v_fma_f32 v79, v168, s8, -v218
	v_mov_b32_e32 v161, v159
	v_exp_f32_e32 v168, v79
	v_fma_f32 v79, v169, s8, -v218
	v_permlane32_swap_b32_e32 v159, v161
	v_exp_f32_e32 v172, v79
	v_fma_f32 v79, v174, s8, -v218
	v_max_f32_e32 v161, v161, v161
	v_max_f32_e32 v159, v159, v159
; DEV f32x4 mfma16(bf16x8 a, bf16x8 b, f32x4 c) { return __builtin_amdgcn_mfma_f32_16x16x32_bf16(a, b, c, 0, 0, 0); }
; template <int KS>
; DEV void attn_chunk(const unsigned char* Kl, const unsigned char* Vl, const bf16x8 (&qf)[2][KS], f32x4 (&O)[2][4], float (&mrun)[2], float (&lrun)[2],
;                     bool masked, int key0, int qw0, float sl2, int lane, int fr, int fq) {
;     ...
;     float ps = 0.f;
; #pragma unroll
;     for (int kt = 0; kt < 4; ++kt)
; #pragma unroll
;       for (int r = 0; r < 4; ++r) { float pvv = __builtin_amdgcn_exp2f(sc[qi][kt][r] - mnew); ps += pvv; sc[qi][kt][r] = pvv; }
;     pf[qi][0] = pack8(sc[qi][0][0], sc[qi][0][1], sc[qi][0][2], sc[qi][0][3], sc[qi][1][0], sc[qi][1][1], sc[qi][1][2], sc[qi][1][3]);
;     pf[qi][1] = pack8(sc[qi][2][0], sc[qi][2][1], sc[qi][2][2], sc[qi][2][3], sc[qi][3][0], sc[qi][3][1], sc[qi][3][2], sc[qi][3][3]);
;     lrun[qi] = lrun[qi] * alpha + ps;
; #pragma unroll
;     for (int dt = 0; dt < 4; ++dt) O[qi][dt] *= alpha;
;   }
; #pragma unroll
;   for (int dt = 0; dt < 4; ++dt)
; #pragma unroll
;     for (int sub = 0; sub < 2; ++sub) {
;       const unsigned char* vp = Vl + ((dt * 16 + fr) * VP + sub * 32 + fq * 4) * 2;
;       u32x2 v0 = *reinterpret_cast<const u32x2*>(vp), v1 = *reinterpret_cast<const u32x2*>(vp + 32);
;       u32x4 vv = {v0[0], v0[1], v1[0], v1[1]};
;       bf16x8 vf = *reinterpret_cast<bf16x8*>(&vv);
;       O[0][dt] = mfma16(vf, pf[0][sub], O[0][dt]); O[1][dt] = mfma16(vf, pf[1][sub], O[1][dt]);
;     }
	v_exp_f32_e32 v170, v79
	v_fma_f32 v79, v175, s8, -v218
	v_max_f32_e32 v159, v159, v161
	v_exp_f32_e32 v174, v79
	v_fma_f32 v79, v176, s8, -v218
	v_exp_f32_e32 v176, v78
	v_mov_b32_e32 v161, v159
	s_nop 1
	v_permlane16_swap_b32_e32 v159, v161
	v_max3_f32 v219, v157, v159, v161
	v_fma_f32 v90, v90, s8, -v219
	v_exp_f32_e32 v186, v79
	v_fma_f32 v79, v177, s8, -v218
	v_pk_mul_f32 v[68:69], v[68:69], v[176:177] op_sel_hi:[1,0]
	v_pk_mul_f32 v[66:67], v[66:67], v[176:177] op_sel_hi:[1,0]
	v_pk_mul_f32 v[72:73], v[72:73], v[176:177] op_sel_hi:[1,0]
	v_pk_mul_f32 v[70:71], v[70:71], v[176:177] op_sel_hi:[1,0]
	v_pk_mul_f32 v[76:77], v[76:77], v[176:177] op_sel_hi:[1,0]
	v_pk_mul_f32 v[74:75], v[74:75], v[176:177] op_sel_hi:[1,0]
	v_pk_mul_f32 v[88:89], v[88:89], v[176:177] op_sel_hi:[1,0]
	v_pk_mul_f32 v[86:87], v[86:87], v[176:177] op_sel_hi:[1,0]
	v_sub_f32_e32 v177, v157, v219
	v_exp_f32_e32 v157, v90
	v_fma_f32 v90, v91, s8, -v219
	v_exp_f32_e32 v161, v90
	v_fma_f32 v90, v92, s8, -v219
	v_exp_f32_e32 v159, v90
	v_fma_f32 v90, v93, s8, -v219
	v_exp_f32_e32 v163, v90
	v_fma_f32 v90, v94, s8, -v219
	v_exp_f32_e32 v167, v90
	v_fma_f32 v90, v95, s8, -v219
	v_exp_f32_e32 v165, v90
	v_fma_f32 v90, v96, s8, -v219
	v_exp_f32_e32 v169, v90
	v_fma_f32 v90, v97, s8, -v219
	v_exp_f32_e32 v173, v90
	v_fma_f32 v90, v98, s8, -v219
	v_exp_f32_e32 v177, v177
	v_exp_f32_e32 v171, v90
	v_fma_f32 v90, v99, s8, -v219
	v_exp_f32_e32 v175, v90
	v_fma_f32 v90, v100, s8, -v219
	v_exp_f32_e32 v187, v90
	v_fma_f32 v90, v101, s8, -v219
	v_exp_f32_e32 v185, v90
	v_fma_f32 v90, v102, s8, -v219
	v_mov_b32_e32 v98, v177
	v_add_u32_e32 v102, 0x8800, v203
	v_pk_mul_f32 v[52:53], v[52:53], v[98:99] op_sel_hi:[1,0]
	v_pk_mul_f32 v[50:51], v[50:51], v[98:99] op_sel_hi:[1,0]
	v_pk_mul_f32 v[56:57], v[56:57], v[98:99] op_sel_hi:[1,0]
	v_pk_mul_f32 v[54:55], v[54:55], v[98:99] op_sel_hi:[1,0]
	v_pk_mul_f32 v[60:61], v[60:61], v[98:99] op_sel_hi:[1,0]
	v_pk_mul_f32 v[58:59], v[58:59], v[98:99] op_sel_hi:[1,0]
	v_pk_mul_f32 v[64:65], v[64:65], v[98:99] op_sel_hi:[1,0]
	v_pk_mul_f32 v[62:63], v[62:63], v[98:99] op_sel_hi:[1,0]
	ds_read2_b64 v[98:101], v102 offset0:128 offset1:132
	v_cvt_pk_bf16_f32 v82, v156, v160
	v_cvt_pk_bf16_f32 v83, v158, v162
	v_cvt_pk_bf16_f32 v84, v166, v164
	v_cvt_pk_bf16_f32 v85, v168, v172
	v_cvt_pk_bf16_f32 v94, v157, v161
	v_cvt_pk_bf16_f32 v95, v159, v163
	v_cvt_pk_bf16_f32 v96, v167, v165
	v_cvt_pk_bf16_f32 v97, v169, v173
	v_exp_f32_e32 v184, v79
	v_fma_f32 v79, v188, s8, -v218
	s_waitcnt lgkmcnt(0)
	v_mfma_f32_16x16x32_bf16 v[66:69], v[98:101], v[82:85], v[66:69]
	v_exp_f32_e32 v194, v79
	v_fma_f32 v79, v189, s8, -v218
	v_exp_f32_e32 v195, v90
	v_mfma_f32_16x16x32_bf16 v[50:53], v[98:101], v[94:97], v[50:53]
	ds_read2_b64 v[98:101], v102 offset0:136 offset1:140
	v_fma_f32 v90, v103, s8, -v219
	v_exp_f32_e32 v192, v79
	v_fma_f32 v79, v190, s8, -v218
	v_exp_f32_e32 v193, v90
	v_fma_f32 v90, v104, s8, -v219
	v_exp_f32_e32 v190, v79
	v_fma_f32 v79, v191, s8, -v218
	v_exp_f32_e32 v191, v90
	v_fma_f32 v90, v105, s8, -v219
	v_exp_f32_e32 v188, v79
	v_exp_f32_e32 v189, v90
	v_cvt_pk_bf16_f32 v78, v170, v174
	v_cvt_pk_bf16_f32 v79, v186, v184
	v_cvt_pk_bf16_f32 v80, v194, v192
	v_cvt_pk_bf16_f32 v81, v190, v188
	v_cvt_pk_bf16_f32 v90, v171, v175
	v_cvt_pk_bf16_f32 v91, v187, v185
	v_cvt_pk_bf16_f32 v92, v195, v193
	v_cvt_pk_bf16_f32 v93, v191, v189
	v_add_u32_e32 v102, 0x9000, v203
	s_waitcnt lgkmcnt(0)
	v_mfma_f32_16x16x32_bf16 v[66:69], v[98:101], v[78:81], v[66:69]
	v_mfma_f32_16x16x32_bf16 v[50:53], v[98:101], v[90:93], v[50:53]
	ds_read2_b64 v[98:101], v102 offset0:160 offset1:164
	s_waitcnt lgkmcnt(0)
	v_mfma_f32_16x16x32_bf16 v[70:73], v[98:101], v[82:85], v[70:73]
	v_mfma_f32_16x16x32_bf16 v[54:57], v[98:101], v[94:97], v[54:57]
	ds_read2_b64 v[98:101], v102 offset0:168 offset1:172
	v_add_u32_e32 v102, 0x9800, v203
	s_waitcnt lgkmcnt(0)
	v_mfma_f32_16x16x32_bf16 v[70:73], v[98:101], v[78:81], v[70:73]
	v_mfma_f32_16x16x32_bf16 v[54:57], v[98:101], v[90:93], v[54:57]
	ds_read2_b64 v[98:101], v102 offset0:192 offset1:196
	s_waitcnt lgkmcnt(0)
	v_mfma_f32_16x16x32_bf16 v[74:77], v[98:101], v[82:85], v[74:77]
	v_mfma_f32_16x16x32_bf16 v[58:61], v[98:101], v[94:97], v[58:61]
	ds_read2_b64 v[98:101], v102 offset0:200 offset1:204
	v_add_u32_e32 v102, 0xa000, v203
	s_waitcnt lgkmcnt(0)
	v_mfma_f32_16x16x32_bf16 v[74:77], v[98:101], v[78:81], v[74:77]
	v_mfma_f32_16x16x32_bf16 v[58:61], v[98:101], v[90:93], v[58:61]
	ds_read2_b64 v[98:101], v102 offset0:224 offset1:228
	s_waitcnt lgkmcnt(0)
	v_mfma_f32_16x16x32_bf16 v[82:85], v[98:101], v[82:85], v[86:89]
	s_nop 2
	ds_read2_b64 v[86:89], v102 offset0:232 offset1:236
	v_mfma_f32_16x16x32_bf16 v[62:65], v[98:101], v[94:97], v[62:65]
	s_waitcnt lgkmcnt(0)
	v_mfma_f32_16x16x32_bf16 v[78:81], v[86:89], v[78:81], v[82:85]
	v_mfma_f32_16x16x32_bf16 v[62:65], v[86:89], v[90:93], v[62:65]
	s_cbranch_vccnz .LBB0_611
	ds_write_b128 v199, v[26:29]
	s_and_saveexec_b64 s[0:1], s[40:41]
	s_cbranch_execz .LBB0_610
	ds_write_b128 v200, v[30:33]
	s_branch .LBB0_610
